# in-proj Q/K-norm epilogue: dropped the 7 per-row-group vmcnt(0) waits that only waited for the previous group's stores (gain vector already loaded and waited once)
# baseline (speedup 1.0000x reference)
; DEV float red4(float s) { s += SWZ_XOR(s, 16); return swapsum(s); }
;   DEV void operator()(f32x4 (&acc)[2][2][4][2], const PgUnit& u, int ui, int wr, int wc, int fr, int fq) const {
;     ...
;         if (nt < 4) {
;           s = red4(s);
;           const float inv = __builtin_amdgcn_rsqf(s * (1.f / 64.f) + EPS) * (nt < 2 ? 0.125f * LOG2E : 1.f);
;           u16* dst = (nt < 2 ? WS{P.ws}.QA() : WS{P.ws}.KA()) + (long)t * 512 + (nt & 1) * 256 + wc * 64;
; #pragma unroll
;           for (int bj = 0; bj < 2; ++bj) {
;             const int c8 = bj * 32 + 8 * fq;
;             const float4 g0 = gg[bj][0], g1 = gg[bj][1];
;             float y[8] = {v[bj][0] * inv * g0.x, v[bj][1] * inv * g0.y, v[bj][2] * inv * g0.z, v[bj][3] * inv * g0.w, v[bj][4] * inv * g1.x, v[bj][5] * inv * g1.y, v[bj][6] * inv * g1.z, v[bj][7] * inv * g1.w};
;             store8bf(dst + c8, y);
;           }
.LBB0_173:
	s_andn2_b64 vcc, exec, s[2:3]
	s_cbranch_vccnz .LBB0_175
	ds_swizzle_b32 v99, v98 offset:swizzle(SWAP,16)
	s_and_b64 s[2:3], s[8:9], exec
	s_cselect_b32 s2, s59, 0x5000000
	v_ashrrev_i32_e32 v97, 31, v96
	s_add_u32 s2, s86, s2
	s_waitcnt lgkmcnt(0)
	v_add_f32_e32 v98, v98, v99
	v_mov_b32_e32 v99, v98
	s_nop 1
	v_permlane32_swap_b32_e32 v98, v99
	v_add_f32_e32 v98, v98, v99
	v_fmamk_f32 v98, v98, 0x3c800000, v227
	v_rsq_f32_e32 v98, v98
	v_lshlrev_b64 v[96:97], 10, v[96:97]
	s_addc_u32 s3, s87, 0
	v_lshl_add_u64 v[96:97], s[2:3], 0, v[96:97]
	v_mul_f32_e32 v98, v168, v98
	v_mul_f32_e32 v92, v92, v98
	v_mul_f32_e32 v88, v88, v98
	s_lshl_b32 s2, s71, 1
	s_mov_b32 s3, s23
	v_mul_f32_e32 v99, v28, v92
	v_mul_f32_e32 v92, v93, v98
	v_mul_f32_e32 v101, v24, v88
	v_mul_f32_e32 v88, v89, v98
	v_lshl_add_u64 v[96:97], v[96:97], 0, s[2:3]
	s_lshl_b32 s2, s65, 1
	v_mul_f32_e32 v100, v29, v92
	v_mul_f32_e32 v92, v94, v98
	v_mul_f32_e32 v102, v25, v88
	v_mul_f32_e32 v88, v90, v98
	v_lshl_add_u64 v[96:97], v[96:97], 0, s[2:3]
	v_mul_f32_e32 v94, v30, v92
	v_mul_f32_e32 v92, v95, v98
	v_mul_f32_e32 v103, v26, v88
	v_mul_f32_e32 v88, v91, v98
	v_mul_f32_e32 v95, v31, v92
	v_mul_f32_e32 v91, v27, v88
	v_lshl_add_u64 v[92:93], v[96:97], 0, v[184:185]
	v_cvt_pk_bf16_f32 v88, v99, v100
	v_mul_f32_e32 v80, v80, v98
	v_cvt_pk_bf16_f32 v89, v94, v95
	v_cvt_pk_bf16_f32 v90, v101, v102
	v_cvt_pk_bf16_f32 v91, v103, v91
	flat_store_dwordx4 v[92:93], v[88:91]
	v_mul_f32_e32 v84, v84, v98
	v_mul_f32_e32 v85, v85, v98
	v_mul_f32_e32 v88, v16, v80
	v_mul_f32_e32 v80, v81, v98
	v_mul_f32_e32 v89, v17, v80
	v_mul_f32_e32 v80, v82, v98
	v_mul_f32_e32 v90, v18, v80
	v_mul_f32_e32 v80, v83, v98
	v_mul_f32_e32 v86, v86, v98
	v_mul_f32_e32 v87, v87, v98
	v_mul_f32_e32 v83, v19, v80
	v_mul_f32_e32 v84, v20, v84
	v_mul_f32_e32 v85, v21, v85
	v_mul_f32_e32 v86, v22, v86
	v_mul_f32_e32 v87, v23, v87
	v_cvt_pk_bf16_f32 v80, v84, v85
	v_cvt_pk_bf16_f32 v81, v86, v87
	v_cvt_pk_bf16_f32 v82, v88, v89
	v_cvt_pk_bf16_f32 v83, v90, v83
	flat_store_dwordx4 v[92:93], v[80:83] offset:64

; DEV float red4(float s) { s += SWZ_XOR(s, 16); return swapsum(s); }
;   DEV void operator()(f32x4 (&acc)[2][2][4][2], const PgUnit& u, int ui, int wr, int wc, int fr, int fq) const {
;     ...
;         if (nt < 4) {
;           s = red4(s);
;           const float inv = __builtin_amdgcn_rsqf(s * (1.f / 64.f) + EPS) * (nt < 2 ? 0.125f * LOG2E : 1.f);
;           u16* dst = (nt < 2 ? WS{P.ws}.QA() : WS{P.ws}.KA()) + (long)t * 512 + (nt & 1) * 256 + wc * 64;
; #pragma unroll
;           for (int bj = 0; bj < 2; ++bj) {
;             const int c8 = bj * 32 + 8 * fq;
;             const float4 g0 = gg[bj][0], g1 = gg[bj][1];
;             float y[8] = {v[bj][0] * inv * g0.x, v[bj][1] * inv * g0.y, v[bj][2] * inv * g0.z, v[bj][3] * inv * g0.w, v[bj][4] * inv * g1.x, v[bj][5] * inv * g1.y, v[bj][6] * inv * g1.z, v[bj][7] * inv * g1.w};
;             store8bf(dst + c8, y);
;           }
.LBB0_203:
	s_andn2_b64 vcc, exec, s[2:3]
	s_cbranch_vccnz .LBB0_205
	ds_swizzle_b32 v83, v82 offset:swizzle(SWAP,16)
	s_and_b64 s[2:3], s[8:9], exec
	s_cselect_b32 s2, s59, 0x5000000
	s_add_u32 s2, s86, s2
	s_addc_u32 s3, s87, 0
	s_waitcnt lgkmcnt(0)
	v_add_f32_e32 v82, v82, v83
	v_mov_b32_e32 v83, v82
	s_nop 1
	v_permlane32_swap_b32_e32 v82, v83
	v_add_f32_e32 v82, v82, v83
	v_fmamk_f32 v82, v82, 0x3c800000, v227
	v_rsq_f32_e32 v82, v82
	v_lshlrev_b64 v[80:81], 10, v[80:81]
	v_lshl_add_u64 v[80:81], s[2:3], 0, v[80:81]
	s_lshl_b32 s2, s71, 1
	v_mul_f32_e32 v82, v168, v82
	v_mul_f32_e32 v76, v76, v82
	v_mul_f32_e32 v72, v72, v82
	s_mov_b32 s3, s23
	v_mul_f32_e32 v83, v28, v76
	v_mul_f32_e32 v76, v77, v82
	v_mul_f32_e32 v85, v24, v72
	v_mul_f32_e32 v72, v73, v82
	v_lshl_add_u64 v[80:81], v[80:81], 0, s[2:3]
	s_lshl_b32 s2, s65, 1
	v_mul_f32_e32 v84, v29, v76
	v_mul_f32_e32 v76, v78, v82
	v_mul_f32_e32 v86, v25, v72
	v_mul_f32_e32 v72, v74, v82
	v_lshl_add_u64 v[80:81], v[80:81], 0, s[2:3]
	v_mul_f32_e32 v78, v30, v76
	v_mul_f32_e32 v76, v79, v82
	v_mul_f32_e32 v87, v26, v72
	v_mul_f32_e32 v72, v75, v82
	v_mul_f32_e32 v79, v31, v76
	v_mul_f32_e32 v75, v27, v72
	v_lshl_add_u64 v[76:77], v[80:81], 0, v[184:185]
	v_cvt_pk_bf16_f32 v72, v83, v84
	v_mul_f32_e32 v64, v64, v82
	v_cvt_pk_bf16_f32 v73, v78, v79
	v_cvt_pk_bf16_f32 v74, v85, v86
	v_cvt_pk_bf16_f32 v75, v87, v75
	flat_store_dwordx4 v[76:77], v[72:75]
	v_mul_f32_e32 v68, v68, v82
	v_mul_f32_e32 v69, v69, v82
	v_mul_f32_e32 v72, v16, v64
	v_mul_f32_e32 v64, v65, v82
	v_mul_f32_e32 v73, v17, v64
	v_mul_f32_e32 v64, v66, v82
	v_mul_f32_e32 v74, v18, v64
	v_mul_f32_e32 v64, v67, v82
	v_mul_f32_e32 v70, v70, v82
	v_mul_f32_e32 v71, v71, v82
	v_mul_f32_e32 v67, v19, v64
	v_mul_f32_e32 v68, v20, v68
	v_mul_f32_e32 v69, v21, v69
	v_mul_f32_e32 v70, v22, v70
	v_mul_f32_e32 v71, v23, v71
	v_cvt_pk_bf16_f32 v64, v68, v69
	v_cvt_pk_bf16_f32 v65, v70, v71
	v_cvt_pk_bf16_f32 v66, v72, v73
	v_cvt_pk_bf16_f32 v67, v74, v67
	flat_store_dwordx4 v[76:77], v[64:67] offset:64

; DEV float red4(float s) { s += SWZ_XOR(s, 16); return swapsum(s); }
;   DEV void operator()(f32x4 (&acc)[2][2][4][2], const PgUnit& u, int ui, int wr, int wc, int fr, int fq) const {
;     ...
;         if (nt < 4) {
;           s = red4(s);
;           const float inv = __builtin_amdgcn_rsqf(s * (1.f / 64.f) + EPS) * (nt < 2 ? 0.125f * LOG2E : 1.f);
;           u16* dst = (nt < 2 ? WS{P.ws}.QA() : WS{P.ws}.KA()) + (long)t * 512 + (nt & 1) * 256 + wc * 64;
; #pragma unroll
;           for (int bj = 0; bj < 2; ++bj) {
;             const int c8 = bj * 32 + 8 * fq;
;             const float4 g0 = gg[bj][0], g1 = gg[bj][1];
;             float y[8] = {v[bj][0] * inv * g0.x, v[bj][1] * inv * g0.y, v[bj][2] * inv * g0.z, v[bj][3] * inv * g0.w, v[bj][4] * inv * g1.x, v[bj][5] * inv * g1.y, v[bj][6] * inv * g1.z, v[bj][7] * inv * g1.w};
;             store8bf(dst + c8, y);
;           }
.LBB0_233:
	s_andn2_b64 vcc, exec, s[2:3]
	s_cbranch_vccnz .LBB0_235
	ds_swizzle_b32 v67, v66 offset:swizzle(SWAP,16)
	s_and_b64 s[2:3], s[8:9], exec
	s_cselect_b32 s2, s59, 0x5000000
	s_add_u32 s2, s86, s2
	s_addc_u32 s3, s87, 0
	s_waitcnt lgkmcnt(0)
	v_add_f32_e32 v66, v66, v67
	v_mov_b32_e32 v67, v66
	s_nop 1
	v_permlane32_swap_b32_e32 v66, v67
	v_add_f32_e32 v66, v66, v67
	v_fmamk_f32 v66, v66, 0x3c800000, v227
	v_rsq_f32_e32 v66, v66
	v_lshlrev_b64 v[64:65], 10, v[64:65]
	v_lshl_add_u64 v[64:65], s[2:3], 0, v[64:65]
	s_lshl_b32 s2, s71, 1
	v_mul_f32_e32 v66, v168, v66
	v_mul_f32_e32 v60, v60, v66
	v_mul_f32_e32 v56, v56, v66
	s_mov_b32 s3, s23
	v_mul_f32_e32 v67, v28, v60
	v_mul_f32_e32 v60, v61, v66
	v_mul_f32_e32 v69, v24, v56
	v_mul_f32_e32 v56, v57, v66
	v_lshl_add_u64 v[64:65], v[64:65], 0, s[2:3]
	s_lshl_b32 s2, s65, 1
	v_mul_f32_e32 v68, v29, v60
	v_mul_f32_e32 v60, v62, v66
	v_mul_f32_e32 v70, v25, v56
	v_mul_f32_e32 v56, v58, v66
	v_lshl_add_u64 v[64:65], v[64:65], 0, s[2:3]
	v_mul_f32_e32 v62, v30, v60
	v_mul_f32_e32 v60, v63, v66
	v_mul_f32_e32 v71, v26, v56
	v_mul_f32_e32 v56, v59, v66
	v_mul_f32_e32 v63, v31, v60
	v_mul_f32_e32 v59, v27, v56
	v_lshl_add_u64 v[60:61], v[64:65], 0, v[184:185]
	v_cvt_pk_bf16_f32 v56, v67, v68
	v_mul_f32_e32 v48, v48, v66
	v_cvt_pk_bf16_f32 v57, v62, v63
	v_cvt_pk_bf16_f32 v58, v69, v70
	v_cvt_pk_bf16_f32 v59, v71, v59
	flat_store_dwordx4 v[60:61], v[56:59]
	v_mul_f32_e32 v52, v52, v66
	v_mul_f32_e32 v53, v53, v66
	v_mul_f32_e32 v56, v16, v48
	v_mul_f32_e32 v48, v49, v66
	v_mul_f32_e32 v57, v17, v48
	v_mul_f32_e32 v48, v50, v66
	v_mul_f32_e32 v58, v18, v48
	v_mul_f32_e32 v48, v51, v66
	v_mul_f32_e32 v54, v54, v66
	v_mul_f32_e32 v55, v55, v66
	v_mul_f32_e32 v51, v19, v48
	v_mul_f32_e32 v52, v20, v52
	v_mul_f32_e32 v53, v21, v53
	v_mul_f32_e32 v54, v22, v54
	v_mul_f32_e32 v55, v23, v55
	v_cvt_pk_bf16_f32 v48, v52, v53
	v_cvt_pk_bf16_f32 v49, v54, v55
	v_cvt_pk_bf16_f32 v50, v56, v57
	v_cvt_pk_bf16_f32 v51, v58, v51
	flat_store_dwordx4 v[60:61], v[48:51] offset:64

; DEV float red4(float s) { s += SWZ_XOR(s, 16); return swapsum(s); }
;   DEV void operator()(f32x4 (&acc)[2][2][4][2], const PgUnit& u, int ui, int wr, int wc, int fr, int fq) const {
;     ...
;         if (nt < 4) {
;           s = red4(s);
;           const float inv = __builtin_amdgcn_rsqf(s * (1.f / 64.f) + EPS) * (nt < 2 ? 0.125f * LOG2E : 1.f);
;           u16* dst = (nt < 2 ? WS{P.ws}.QA() : WS{P.ws}.KA()) + (long)t * 512 + (nt & 1) * 256 + wc * 64;
; #pragma unroll
;           for (int bj = 0; bj < 2; ++bj) {
;             const int c8 = bj * 32 + 8 * fq;
;             const float4 g0 = gg[bj][0], g1 = gg[bj][1];
;             float y[8] = {v[bj][0] * inv * g0.x, v[bj][1] * inv * g0.y, v[bj][2] * inv * g0.z, v[bj][3] * inv * g0.w, v[bj][4] * inv * g1.x, v[bj][5] * inv * g1.y, v[bj][6] * inv * g1.z, v[bj][7] * inv * g1.w};
;             store8bf(dst + c8, y);
;           }
.LBB0_263:
	s_andn2_b64 vcc, exec, s[2:3]
	s_cbranch_vccnz .LBB0_265
	ds_swizzle_b32 v51, v50 offset:swizzle(SWAP,16)
	s_and_b64 s[2:3], s[8:9], exec
	s_cselect_b32 s2, s59, 0x5000000
	s_add_u32 s2, s86, s2
	s_addc_u32 s3, s87, 0
	s_waitcnt lgkmcnt(0)
	v_add_f32_e32 v50, v50, v51
	v_mov_b32_e32 v51, v50
	s_nop 1
	v_permlane32_swap_b32_e32 v50, v51
	v_add_f32_e32 v50, v50, v51
	v_fmamk_f32 v50, v50, 0x3c800000, v227
	v_rsq_f32_e32 v50, v50
	v_lshlrev_b64 v[48:49], 10, v[48:49]
	v_lshl_add_u64 v[48:49], s[2:3], 0, v[48:49]
	s_lshl_b32 s2, s71, 1
	v_mul_f32_e32 v50, v168, v50
	v_mul_f32_e32 v44, v44, v50
	v_mul_f32_e32 v40, v40, v50
	s_mov_b32 s3, s23
	v_mul_f32_e32 v51, v28, v44
	v_mul_f32_e32 v44, v45, v50
	v_mul_f32_e32 v53, v24, v40
	v_mul_f32_e32 v40, v41, v50
	v_lshl_add_u64 v[48:49], v[48:49], 0, s[2:3]
	s_lshl_b32 s2, s65, 1
	v_mul_f32_e32 v52, v29, v44
	v_mul_f32_e32 v44, v46, v50
	v_mul_f32_e32 v54, v25, v40
	v_mul_f32_e32 v40, v42, v50
	v_lshl_add_u64 v[48:49], v[48:49], 0, s[2:3]
	v_mul_f32_e32 v46, v30, v44
	v_mul_f32_e32 v44, v47, v50
	v_mul_f32_e32 v55, v26, v40
	v_mul_f32_e32 v40, v43, v50
	v_mul_f32_e32 v47, v31, v44
	v_mul_f32_e32 v43, v27, v40
	v_lshl_add_u64 v[44:45], v[48:49], 0, v[184:185]
	v_cvt_pk_bf16_f32 v40, v51, v52
	v_mul_f32_e32 v32, v32, v50
	v_cvt_pk_bf16_f32 v41, v46, v47
	v_cvt_pk_bf16_f32 v42, v53, v54
	v_cvt_pk_bf16_f32 v43, v55, v43
	flat_store_dwordx4 v[44:45], v[40:43]
	v_mul_f32_e32 v36, v36, v50
	v_mul_f32_e32 v37, v37, v50
	v_mul_f32_e32 v40, v16, v32
	v_mul_f32_e32 v32, v33, v50
	v_mul_f32_e32 v41, v17, v32
	v_mul_f32_e32 v32, v34, v50
	v_mul_f32_e32 v42, v18, v32
	v_mul_f32_e32 v32, v35, v50
	v_mul_f32_e32 v38, v38, v50
	v_mul_f32_e32 v39, v39, v50
	v_mul_f32_e32 v35, v19, v32
	v_mul_f32_e32 v36, v20, v36
	v_mul_f32_e32 v37, v21, v37
	v_mul_f32_e32 v38, v22, v38
	v_mul_f32_e32 v39, v23, v39
	v_cvt_pk_bf16_f32 v32, v36, v37
	v_cvt_pk_bf16_f32 v33, v38, v39
	v_cvt_pk_bf16_f32 v34, v40, v41
	v_cvt_pk_bf16_f32 v35, v42, v35
	flat_store_dwordx4 v[44:45], v[32:35] offset:64

; DEV float red4(float s) { s += SWZ_XOR(s, 16); return swapsum(s); }
;   DEV void operator()(f32x4 (&acc)[2][2][4][2], const PgUnit& u, int ui, int wr, int wc, int fr, int fq) const {
;     ...
;         if (nt < 4) {
;           s = red4(s);
;           const float inv = __builtin_amdgcn_rsqf(s * (1.f / 64.f) + EPS) * (nt < 2 ? 0.125f * LOG2E : 1.f);
;           u16* dst = (nt < 2 ? WS{P.ws}.QA() : WS{P.ws}.KA()) + (long)t * 512 + (nt & 1) * 256 + wc * 64;
; #pragma unroll
;           for (int bj = 0; bj < 2; ++bj) {
;             const int c8 = bj * 32 + 8 * fq;
;             const float4 g0 = gg[bj][0], g1 = gg[bj][1];
;             float y[8] = {v[bj][0] * inv * g0.x, v[bj][1] * inv * g0.y, v[bj][2] * inv * g0.z, v[bj][3] * inv * g0.w, v[bj][4] * inv * g1.x, v[bj][5] * inv * g1.y, v[bj][6] * inv * g1.z, v[bj][7] * inv * g1.w};
;             store8bf(dst + c8, y);
;           }
.LBB0_293:
	s_andn2_b64 vcc, exec, s[2:3]
	s_cbranch_vccnz .LBB0_98
	ds_swizzle_b32 v35, v34 offset:swizzle(SWAP,16)
	s_and_b64 s[2:3], s[8:9], exec
	s_cselect_b32 s2, s59, 0x5000000
	s_add_u32 s2, s86, s2
	s_addc_u32 s3, s87, 0
	s_waitcnt lgkmcnt(0)
	v_add_f32_e32 v34, v34, v35
	v_mov_b32_e32 v35, v34
	s_nop 1
	v_permlane32_swap_b32_e32 v34, v35
	v_add_f32_e32 v34, v34, v35
	v_fmamk_f32 v34, v34, 0x3c800000, v227
	v_rsq_f32_e32 v34, v34
	v_lshlrev_b64 v[32:33], 10, v[32:33]
	v_lshl_add_u64 v[32:33], s[2:3], 0, v[32:33]
	s_lshl_b32 s22, s71, 1
	v_mul_f32_e32 v34, v168, v34
	v_mul_f32_e32 v12, v12, v34
	v_mul_f32_e32 v8, v8, v34
	v_mul_f32_e32 v28, v28, v12
	v_mul_f32_e32 v12, v13, v34
	v_mul_f32_e32 v24, v24, v8
	v_mul_f32_e32 v8, v9, v34
	v_lshl_add_u64 v[32:33], v[32:33], 0, s[22:23]
	s_lshl_b32 s22, s65, 1
	v_mul_f32_e32 v29, v29, v12
	v_mul_f32_e32 v12, v14, v34
	v_mul_f32_e32 v25, v25, v8
	v_mul_f32_e32 v8, v10, v34
	v_lshl_add_u64 v[32:33], v[32:33], 0, s[22:23]
	v_mul_f32_e32 v14, v30, v12
	v_mul_f32_e32 v12, v15, v34
	v_mul_f32_e32 v26, v26, v8
	v_mul_f32_e32 v8, v11, v34
	v_mul_f32_e32 v15, v31, v12
	v_mul_f32_e32 v11, v27, v8
	v_lshl_add_u64 v[12:13], v[32:33], 0, v[184:185]
	v_cvt_pk_bf16_f32 v8, v28, v29
	v_mul_f32_e32 v0, v0, v34
	v_cvt_pk_bf16_f32 v9, v14, v15
	v_cvt_pk_bf16_f32 v10, v24, v25
	v_cvt_pk_bf16_f32 v11, v26, v11
	flat_store_dwordx4 v[12:13], v[8:11]
	v_mul_f32_e32 v4, v4, v34
	v_mul_f32_e32 v5, v5, v34
	v_mul_f32_e32 v8, v16, v0
	v_mul_f32_e32 v0, v1, v34
	v_mul_f32_e32 v9, v17, v0
	v_mul_f32_e32 v0, v2, v34
	v_mul_f32_e32 v10, v18, v0
	v_mul_f32_e32 v0, v3, v34
	v_mul_f32_e32 v6, v6, v34
	v_mul_f32_e32 v7, v7, v34
	v_mul_f32_e32 v3, v19, v0
	v_mul_f32_e32 v4, v20, v4
	v_mul_f32_e32 v5, v21, v5
	v_mul_f32_e32 v6, v22, v6
	v_mul_f32_e32 v7, v23, v7
	v_cvt_pk_bf16_f32 v0, v4, v5
	v_cvt_pk_bf16_f32 v1, v6, v7
	v_cvt_pk_bf16_f32 v2, v8, v9
	v_cvt_pk_bf16_f32 v3, v10, v3
	flat_store_dwordx4 v[12:13], v[0:3] offset:64
	s_branch .LBB0_98

; DEV float red4(float s) { s += SWZ_XOR(s, 16); return swapsum(s); }
;   DEV void operator()(f32x4 (&acc)[2][2][4][2], const PgUnit& u, int ui, int wr, int wc, int fr, int fq) const {
;     ...
;         if (nt < 4) {
;           s = red4(s);
;           const float inv = __builtin_amdgcn_rsqf(s * (1.f / 64.f) + EPS) * (nt < 2 ? 0.125f * LOG2E : 1.f);
;           u16* dst = (nt < 2 ? WS{P.ws}.QA() : WS{P.ws}.KA()) + (long)t * 512 + (nt & 1) * 256 + wc * 64;
; #pragma unroll
;           for (int bj = 0; bj < 2; ++bj) {
;             const int c8 = bj * 32 + 8 * fq;
;             const float4 g0 = gg[bj][0], g1 = gg[bj][1];
;             float y[8] = {v[bj][0] * inv * g0.x, v[bj][1] * inv * g0.y, v[bj][2] * inv * g0.z, v[bj][3] * inv * g0.w, v[bj][4] * inv * g1.x, v[bj][5] * inv * g1.y, v[bj][6] * inv * g1.z, v[bj][7] * inv * g1.w};
;             store8bf(dst + c8, y);
;           }
.LBB0_318:
	ds_swizzle_b32 v131, v130 offset:swizzle(SWAP,16)
	s_and_b64 s[2:3], s[8:9], exec
	s_cselect_b32 s2, s59, 0x5000000
	v_ashrrev_i32_e32 v129, 31, v128
	s_add_u32 s2, s86, s2
	s_waitcnt lgkmcnt(0)
	v_add_f32_e32 v130, v130, v131
	v_mov_b32_e32 v131, v130
	s_nop 1
	v_permlane32_swap_b32_e32 v130, v131
	v_add_f32_e32 v130, v130, v131
	v_fmamk_f32 v130, v130, 0x3c800000, v227
	v_rsq_f32_e32 v130, v130
	v_lshlrev_b64 v[128:129], 10, v[128:129]
	s_addc_u32 s3, s87, 0
	v_lshl_add_u64 v[128:129], s[2:3], 0, v[128:129]
	v_mul_f32_e32 v130, v168, v130
	v_mul_f32_e32 v124, v124, v130
	v_mul_f32_e32 v120, v120, v130
	s_lshl_b32 s2, s71, 1
	s_mov_b32 s3, s23
	v_mul_f32_e32 v131, v28, v124
	v_mul_f32_e32 v124, v125, v130
	v_mul_f32_e32 v133, v24, v120
	v_mul_f32_e32 v120, v121, v130
	v_lshl_add_u64 v[128:129], v[128:129], 0, s[2:3]
	s_lshl_b32 s2, s65, 1
	v_mul_f32_e32 v132, v29, v124
	v_mul_f32_e32 v124, v126, v130
	v_mul_f32_e32 v134, v25, v120
	v_mul_f32_e32 v120, v122, v130
	v_lshl_add_u64 v[128:129], v[128:129], 0, s[2:3]
	v_mul_f32_e32 v126, v30, v124
	v_mul_f32_e32 v124, v127, v130
	v_mul_f32_e32 v135, v26, v120
	v_mul_f32_e32 v120, v123, v130
	v_mul_f32_e32 v127, v31, v124
	v_mul_f32_e32 v123, v27, v120
	v_lshl_add_u64 v[124:125], v[128:129], 0, v[184:185]
	v_cvt_pk_bf16_f32 v120, v131, v132
	v_mul_f32_e32 v112, v112, v130
	v_cvt_pk_bf16_f32 v121, v126, v127
	v_cvt_pk_bf16_f32 v122, v133, v134
	v_cvt_pk_bf16_f32 v123, v135, v123
	flat_store_dwordx4 v[124:125], v[120:123]
	v_mul_f32_e32 v116, v116, v130
	v_mul_f32_e32 v117, v117, v130
	v_mul_f32_e32 v120, v16, v112
	v_mul_f32_e32 v112, v113, v130
	v_mul_f32_e32 v121, v17, v112
	v_mul_f32_e32 v112, v114, v130
	v_mul_f32_e32 v122, v18, v112
	v_mul_f32_e32 v112, v115, v130
	v_mul_f32_e32 v118, v118, v130
	v_mul_f32_e32 v119, v119, v130
	v_mul_f32_e32 v115, v19, v112
	v_mul_f32_e32 v116, v20, v116
	v_mul_f32_e32 v117, v21, v117
	v_mul_f32_e32 v118, v22, v118
	v_mul_f32_e32 v119, v23, v119
	v_cvt_pk_bf16_f32 v112, v116, v117
	v_cvt_pk_bf16_f32 v113, v118, v119
	v_cvt_pk_bf16_f32 v114, v120, v121
	v_cvt_pk_bf16_f32 v115, v122, v115
	flat_store_dwordx4 v[124:125], v[112:115] offset:64
	s_and_b64 vcc, exec, s[10:11]
	s_mov_b64 s[2:3], -1
	s_cbranch_vccnz .LBB0_142

; DEV float red4(float s) { s += SWZ_XOR(s, 16); return swapsum(s); }
;   DEV void operator()(f32x4 (&acc)[2][2][4][2], const PgUnit& u, int ui, int wr, int wc, int fr, int fq) const {
;     ...
;         if (nt < 4) {
;           s = red4(s);
;           const float inv = __builtin_amdgcn_rsqf(s * (1.f / 64.f) + EPS) * (nt < 2 ? 0.125f * LOG2E : 1.f);
;           u16* dst = (nt < 2 ? WS{P.ws}.QA() : WS{P.ws}.KA()) + (long)t * 512 + (nt & 1) * 256 + wc * 64;
; #pragma unroll
;           for (int bj = 0; bj < 2; ++bj) {
;             const int c8 = bj * 32 + 8 * fq;
;             const float4 g0 = gg[bj][0], g1 = gg[bj][1];
;             float y[8] = {v[bj][0] * inv * g0.x, v[bj][1] * inv * g0.y, v[bj][2] * inv * g0.z, v[bj][3] * inv * g0.w, v[bj][4] * inv * g1.x, v[bj][5] * inv * g1.y, v[bj][6] * inv * g1.z, v[bj][7] * inv * g1.w};
;             store8bf(dst + c8, y);
;           }
.LBB0_343:
	ds_swizzle_b32 v115, v114 offset:swizzle(SWAP,16)
	s_and_b64 s[2:3], s[8:9], exec
	s_cselect_b32 s2, s59, 0x5000000
	v_ashrrev_i32_e32 v113, 31, v112
	s_add_u32 s2, s86, s2
	s_waitcnt lgkmcnt(0)
	v_add_f32_e32 v114, v114, v115
	v_mov_b32_e32 v115, v114
	s_nop 1
	v_permlane32_swap_b32_e32 v114, v115
	v_add_f32_e32 v114, v114, v115
	v_fmamk_f32 v114, v114, 0x3c800000, v227
	v_rsq_f32_e32 v114, v114
	v_lshlrev_b64 v[112:113], 10, v[112:113]
	s_addc_u32 s3, s87, 0
	v_lshl_add_u64 v[112:113], s[2:3], 0, v[112:113]
	v_mul_f32_e32 v114, v168, v114
	v_mul_f32_e32 v108, v108, v114
	v_mul_f32_e32 v104, v104, v114
	s_lshl_b32 s2, s71, 1
	s_mov_b32 s3, s23
	v_mul_f32_e32 v115, v28, v108
	v_mul_f32_e32 v108, v109, v114
	v_mul_f32_e32 v117, v24, v104
	v_mul_f32_e32 v104, v105, v114
	v_lshl_add_u64 v[112:113], v[112:113], 0, s[2:3]
	s_lshl_b32 s2, s65, 1
	v_mul_f32_e32 v116, v29, v108
	v_mul_f32_e32 v108, v110, v114
	v_mul_f32_e32 v118, v25, v104
	v_mul_f32_e32 v104, v106, v114
	v_lshl_add_u64 v[112:113], v[112:113], 0, s[2:3]
	v_mul_f32_e32 v110, v30, v108
	v_mul_f32_e32 v108, v111, v114
	v_mul_f32_e32 v119, v26, v104
	v_mul_f32_e32 v104, v107, v114
	v_mul_f32_e32 v111, v31, v108
	v_mul_f32_e32 v107, v27, v104
	v_lshl_add_u64 v[108:109], v[112:113], 0, v[184:185]
	v_cvt_pk_bf16_f32 v104, v115, v116
	v_mul_f32_e32 v96, v96, v114
	v_cvt_pk_bf16_f32 v105, v110, v111
	v_cvt_pk_bf16_f32 v106, v117, v118
	v_cvt_pk_bf16_f32 v107, v119, v107
	flat_store_dwordx4 v[108:109], v[104:107]
	v_mul_f32_e32 v100, v100, v114
	v_mul_f32_e32 v101, v101, v114
	v_mul_f32_e32 v104, v16, v96
	v_mul_f32_e32 v96, v97, v114
	v_mul_f32_e32 v105, v17, v96
	v_mul_f32_e32 v96, v98, v114
	v_mul_f32_e32 v106, v18, v96
	v_mul_f32_e32 v96, v99, v114
	v_mul_f32_e32 v102, v102, v114
	v_mul_f32_e32 v103, v103, v114
	v_mul_f32_e32 v99, v19, v96
	v_mul_f32_e32 v100, v20, v100
	v_mul_f32_e32 v101, v21, v101
	v_mul_f32_e32 v102, v22, v102
	v_mul_f32_e32 v103, v23, v103
	v_cvt_pk_bf16_f32 v96, v100, v101
	v_cvt_pk_bf16_f32 v97, v102, v103
	v_cvt_pk_bf16_f32 v98, v104, v105
	v_cvt_pk_bf16_f32 v99, v106, v99
	flat_store_dwordx4 v[108:109], v[96:99] offset:64
	s_and_b64 vcc, exec, s[10:11]
	s_mov_b64 s[2:3], -1
	s_cbranch_vccnz .LBB0_147
